# SEAM(5) grid barrier replaced by per-row-panel point-to-point counters (4 producers per P6 consumer)
# baseline (speedup 1.0000x reference)
.LBB0_2092:
	s_cmp_gt_i32 s83, 6
	s_cselect_b64 s[0:1], -1, 0
	s_and_b64 s[2:3], s[6:7], s[0:1]
	s_andn2_b64 vcc, exec, s[2:3]
	s_cbranch_vccnz .LBB0_2146
	s_waitcnt vmcnt(0) lgkmcnt(0)
	s_barrier
	s_and_saveexec_b64 s[4:5], s[52:53]
	s_cbranch_execz .Lp2p5_end
	s_and_b32 s2, s86, 7
	s_lshl_b32 s2, s2, 3
	s_bfe_u32 s3, s86, 0x30003
	s_or_b32 s2, s2, s3
	s_lshl_b32 s2, s2, 7
	s_add_u32 s6, s80, 0xd000
	s_addc_u32 s7, s81, 0
	s_add_u32 s6, s6, s2
	s_addc_u32 s7, s7, 0
	v_mov_b32_e32 v1, 1
	v_mov_b32_e32 v2, 0
	buffer_wbl2 sc1
	s_waitcnt vmcnt(0)
	global_atomic_add v2, v1, s[6:7]
	s_mov_b32 s3, 0
.Lp2p5_poll:
	global_load_dword v3, v2, s[6:7] sc1
	s_waitcnt vmcnt(0)
	v_readfirstlane_b32 s8, v3
	s_cmp_ge_u32 s8, 4
	s_cbranch_scc1 .Lp2p5_ok
	s_sleep 1
	s_add_i32 s3, s3, 1
	s_cmp_lt_u32 s3, 0x2000
	s_cbranch_scc1 .Lp2p5_poll
.Lp2p5_ok:
	buffer_inv sc1
.Lp2p5_end:
	s_or_b64 exec, exec, s[4:5]
	s_waitcnt vmcnt(0) lgkmcnt(0)
	s_barrier
.LBB0_2146:
	s_cmp_lt_i32 s82, 7
	s_cselect_b64 s[2:3], -1, 0
	s_cmpk_eq_i32 s88, 0x100
	s_cselect_b64 s[4:5], -1, 0
	s_and_b64 s[4:5], s[4:5], s[2:3]
	s_cmp_gt_i32 s83, 7
	s_cselect_b64 s[6:7], -1, 0
	s_and_b64 s[10:11], s[4:5], s[6:7]
	s_and_b64 s[8:9], s[2:3], s[0:1]
	s_mov_b64 s[4:5], -1
	s_andn2_b64 vcc, exec, s[8:9]
	s_xor_b64 s[10:11], s[10:11], -1
	s_cbranch_vccnz .LBB0_2233
	s_add_u32 s33, s80, 0x4700000
	s_addc_u32 s44, s81, 0
	s_add_u32 s45, s80, 0xf00000
	s_addc_u32 s46, s81, 0
	s_and_b64 vcc, exec, s[10:11]
	s_cbranch_vccz .LBB0_2184
	v_mov_b32_e32 v14, v0
	s_cmpk_lt_i32 s86, 0x100
	s_cselect_b64 s[0:1], -1, 0
	s_cmpk_gt_i32 s86, 0xff
	v_readfirstlane_b32 s4, v14
	s_cbranch_scc1 .LBB0_2150
	s_ashr_i32 s2, s86, 31
	s_lshr_b32 s2, s2, 29
	s_add_i32 s2, s86, s2
	s_ashr_i32 s3, s2, 3
	s_and_b32 s2, s2, -8
	s_sub_i32 s2, s86, s2
	s_lshr_b32 s5, s2, 31
	s_or_b32 s5, s5, 32
	s_mul_i32 s2, s5, s2
	s_add_i32 s2, s2, s3
	s_ashr_i32 s3, s2, 31
	s_lshr_b32 s3, s3, 27
	s_add_i32 s3, s2, s3
	s_ashr_i32 s5, s3, 5
	s_lshl_b32 s5, s5, 3
	s_sub_i32 s12, 64, s5
	s_min_u32 s13, s12, 8
	s_andn2_b32 s3, s3, 31
	s_sub_i32 s14, s2, s3
	v_cvt_f32_ubyte0_e32 v2, s13
	v_cvt_f32_i32_e32 v1, s14
	v_rcp_iflag_f32_e32 v3, v2
	s_ashr_i32 s2, s14, 30
	s_or_b32 s12, s2, 1
	v_mul_f32_e32 v3, v1, v3
	v_trunc_f32_e32 v3, v3
	v_fma_f32 v1, -v3, v2, v1
	v_cvt_i32_f32_e32 v3, v3
	v_cmp_ge_f32_e64 s[2:3], |v1|, v2
	s_and_b64 s[2:3], s[2:3], exec
	s_cselect_b32 s2, s12, 0
	v_readfirstlane_b32 s3, v3
	s_add_i32 s2, s3, s2
	s_sext_i32_i8 s12, s2
	s_mul_i32 s2, s2, s13
	s_sub_i32 s2, s14, s2
	s_sext_i32_i8 s2, s2
	s_add_i32 s16, s5, s2
